# P4 final epilogue by hand: 16 gate loads issued up front and waited once, stores one group behind their ds_bpermutes
# speedup vs baseline: 1.0051x; 1.0031x over previous
.LBB0_549:
	s_cmp_lg_u32 s58, 0
	s_cselect_b64 s[6:7], -1, 0
	s_and_b64 vcc, exec, s[6:7]
	s_cbranch_vccz .LBB0_557
	s_lshl_b32 s3, s42, 3
	s_lshl_b32 s2, s40, 5
	s_add_i32 s3, s3, s21
	s_add_i32 s2, s3, s2
	s_ashr_i32 s3, s2, 31
	s_lshl_b64 s[2:3], s[2:3], 13
	v_lshl_add_u64 v[134:135], v[200:201], 0, s[2:3]
	s_mov_b64 s[2:3], 0x1000
	v_lshl_add_u64 v[136:137], v[134:135], 0, s[2:3]
	global_load_dwordx2 v[150:151], v[134:135], off
	global_load_dwordx2 v[152:153], v[134:135], off offset:512
	global_load_dwordx2 v[154:155], v[134:135], off offset:1024
	global_load_dwordx2 v[156:157], v[134:135], off offset:1536
	global_load_dwordx2 v[158:159], v[134:135], off offset:2048
	global_load_dwordx2 v[160:161], v[134:135], off offset:2560
	global_load_dwordx2 v[162:163], v[134:135], off offset:3072
	global_load_dwordx2 v[164:165], v[134:135], off offset:3584
	global_load_dwordx2 v[166:167], v[136:137], off
	global_load_dwordx2 v[168:169], v[136:137], off offset:512
	global_load_dwordx2 v[170:171], v[136:137], off offset:1024
	global_load_dwordx2 v[172:173], v[136:137], off offset:1536
	global_load_dwordx2 v[174:175], v[136:137], off offset:2048
	global_load_dwordx2 v[176:177], v[136:137], off offset:2560
	global_load_dwordx2 v[178:179], v[136:137], off offset:3072
	global_load_dwordx2 v[180:181], v[136:137], off offset:3584
	v_lshl_add_u32 v138, s40, 8, v242
	v_lshl_or_b32 v148, s42, 8, v243
	v_ashrrev_i32_e32 v139, 31, v138
	v_ashrrev_i32_e32 v149, 31, v148
	v_lshlrev_b64 v[148:149], 1, v[148:149]
	v_lshlrev_b64 v[138:139], 11, v[138:139]
	v_lshl_add_u64 v[138:139], s[10:11], 0, v[138:139]
	v_lshl_add_u64 v[138:139], v[138:139], 0, v[148:149]
	s_waitcnt vmcnt(0)
	v_mov_b64_e32 v[140:141], v[138:139]
	v_cvt_f32_ubyte0_e32 v182, v150
	v_cvt_f32_ubyte1_e32 v183, v150
	v_cvt_f32_ubyte2_e32 v184, v150
	v_cvt_f32_ubyte3_e32 v185, v150
	v_cvt_f32_ubyte0_e32 v186, v151
	v_cvt_f32_ubyte1_e32 v187, v151
	v_cvt_f32_ubyte2_e32 v188, v151
	v_cvt_f32_ubyte3_e32 v189, v151
	v_pk_mul_f32 v[182:183], v[182:183], s[20:21] op_sel_hi:[1,0]
	v_pk_mul_f32 v[184:185], v[184:185], s[20:21] op_sel_hi:[1,0]
	v_pk_mul_f32 v[186:187], v[186:187], s[20:21] op_sel_hi:[1,0]
	v_pk_mul_f32 v[188:189], v[188:189], s[20:21] op_sel_hi:[1,0]
	v_pk_mul_f32 v[182:183], v[130:131], v[182:183]
	v_pk_mul_f32 v[184:185], v[132:133], v[184:185]
	v_pk_mul_f32 v[186:187], v[126:127], v[186:187]
	v_pk_mul_f32 v[188:189], v[128:129], v[188:189]
	v_cvt_pk_bf16_f32 v190, v182, v183
	v_cvt_pk_bf16_f32 v191, v184, v185
	v_cvt_pk_bf16_f32 v192, v186, v187
	v_cvt_pk_bf16_f32 v193, v188, v189
	ds_bpermute_b32 v194, v241, v190
	ds_bpermute_b32 v195, v241, v191
	ds_bpermute_b32 v196, v241, v192
	ds_bpermute_b32 v197, v241, v193
	v_cvt_f32_ubyte0_e32 v222, v152
	v_cvt_f32_ubyte1_e32 v223, v152
	v_cvt_f32_ubyte2_e32 v224, v152
	v_cvt_f32_ubyte3_e32 v225, v152
	v_cvt_f32_ubyte0_e32 v226, v153
	v_cvt_f32_ubyte1_e32 v227, v153
	v_cvt_f32_ubyte2_e32 v228, v153
	v_cvt_f32_ubyte3_e32 v229, v153
	v_pk_mul_f32 v[222:223], v[222:223], s[20:21] op_sel_hi:[1,0]
	v_pk_mul_f32 v[224:225], v[224:225], s[20:21] op_sel_hi:[1,0]
	v_pk_mul_f32 v[226:227], v[226:227], s[20:21] op_sel_hi:[1,0]
	v_pk_mul_f32 v[228:229], v[228:229], s[20:21] op_sel_hi:[1,0]
	v_pk_mul_f32 v[222:223], v[98:99], v[222:223]
	v_pk_mul_f32 v[224:225], v[100:101], v[224:225]
	v_pk_mul_f32 v[226:227], v[94:95], v[226:227]
	v_pk_mul_f32 v[228:229], v[96:97], v[228:229]
	v_cvt_pk_bf16_f32 v144, v222, v223
	v_cvt_pk_bf16_f32 v145, v224, v225
	v_cvt_pk_bf16_f32 v146, v226, v227
	v_cvt_pk_bf16_f32 v147, v228, v229
	ds_bpermute_b32 v250, v241, v144
	ds_bpermute_b32 v251, v241, v145
	ds_bpermute_b32 v252, v241, v146
	ds_bpermute_b32 v253, v241, v147
	s_waitcnt lgkmcnt(4)
	global_store_dwordx4 v[140:141], v[194:197], off nt
	s_mov_b64 s[2:3], 0x8000
	v_lshl_add_u64 v[142:143], v[138:139], 0, s[2:3]
	v_cvt_f32_ubyte0_e32 v182, v154
	v_cvt_f32_ubyte1_e32 v183, v154
	v_cvt_f32_ubyte2_e32 v184, v154
	v_cvt_f32_ubyte3_e32 v185, v154
	v_cvt_f32_ubyte0_e32 v186, v155
	v_cvt_f32_ubyte1_e32 v187, v155
	v_cvt_f32_ubyte2_e32 v188, v155
	v_cvt_f32_ubyte3_e32 v189, v155
	v_pk_mul_f32 v[182:183], v[182:183], s[20:21] op_sel_hi:[1,0]
	v_pk_mul_f32 v[184:185], v[184:185], s[20:21] op_sel_hi:[1,0]
	v_pk_mul_f32 v[186:187], v[186:187], s[20:21] op_sel_hi:[1,0]
	v_pk_mul_f32 v[188:189], v[188:189], s[20:21] op_sel_hi:[1,0]
	v_pk_mul_f32 v[182:183], v[122:123], v[182:183]
	v_pk_mul_f32 v[184:185], v[124:125], v[184:185]
	v_pk_mul_f32 v[186:187], v[118:119], v[186:187]
	v_pk_mul_f32 v[188:189], v[120:121], v[188:189]
	v_cvt_pk_bf16_f32 v190, v182, v183
	v_cvt_pk_bf16_f32 v191, v184, v185
	v_cvt_pk_bf16_f32 v192, v186, v187
	v_cvt_pk_bf16_f32 v193, v188, v189
	ds_bpermute_b32 v194, v241, v190
	ds_bpermute_b32 v195, v241, v191
	ds_bpermute_b32 v196, v241, v192
	ds_bpermute_b32 v197, v241, v193
	s_waitcnt lgkmcnt(4)
	global_store_dwordx4 v[140:141], v[250:253], off offset:256 nt
	v_cvt_f32_ubyte0_e32 v222, v156
	v_cvt_f32_ubyte1_e32 v223, v156
	v_cvt_f32_ubyte2_e32 v224, v156
	v_cvt_f32_ubyte3_e32 v225, v156
	v_cvt_f32_ubyte0_e32 v226, v157
	v_cvt_f32_ubyte1_e32 v227, v157
	v_cvt_f32_ubyte2_e32 v228, v157
	v_cvt_f32_ubyte3_e32 v229, v157
	v_pk_mul_f32 v[222:223], v[222:223], s[20:21] op_sel_hi:[1,0]
	v_pk_mul_f32 v[224:225], v[224:225], s[20:21] op_sel_hi:[1,0]
	v_pk_mul_f32 v[226:227], v[226:227], s[20:21] op_sel_hi:[1,0]
	v_pk_mul_f32 v[228:229], v[228:229], s[20:21] op_sel_hi:[1,0]
	v_pk_mul_f32 v[222:223], v[90:91], v[222:223]
	v_pk_mul_f32 v[224:225], v[92:93], v[224:225]
	v_pk_mul_f32 v[226:227], v[86:87], v[226:227]
	v_pk_mul_f32 v[228:229], v[88:89], v[228:229]
	v_cvt_pk_bf16_f32 v144, v222, v223
	v_cvt_pk_bf16_f32 v145, v224, v225
	v_cvt_pk_bf16_f32 v146, v226, v227
	v_cvt_pk_bf16_f32 v147, v228, v229
	ds_bpermute_b32 v250, v241, v144
	ds_bpermute_b32 v251, v241, v145
	ds_bpermute_b32 v252, v241, v146
	ds_bpermute_b32 v253, v241, v147
	s_waitcnt lgkmcnt(4)
	global_store_dwordx4 v[142:143], v[194:197], off nt
	s_mov_b64 s[2:3], 0x10000
	v_lshl_add_u64 v[140:141], v[138:139], 0, s[2:3]
	v_cvt_f32_ubyte0_e32 v182, v158
	v_cvt_f32_ubyte1_e32 v183, v158
	v_cvt_f32_ubyte2_e32 v184, v158
	v_cvt_f32_ubyte3_e32 v185, v158
	v_cvt_f32_ubyte0_e32 v186, v159
	v_cvt_f32_ubyte1_e32 v187, v159
	v_cvt_f32_ubyte2_e32 v188, v159
	v_cvt_f32_ubyte3_e32 v189, v159
	v_pk_mul_f32 v[182:183], v[182:183], s[20:21] op_sel_hi:[1,0]
	v_pk_mul_f32 v[184:185], v[184:185], s[20:21] op_sel_hi:[1,0]
	v_pk_mul_f32 v[186:187], v[186:187], s[20:21] op_sel_hi:[1,0]
	v_pk_mul_f32 v[188:189], v[188:189], s[20:21] op_sel_hi:[1,0]
	v_pk_mul_f32 v[182:183], v[114:115], v[182:183]
	v_pk_mul_f32 v[184:185], v[116:117], v[184:185]
	v_pk_mul_f32 v[186:187], v[110:111], v[186:187]
	v_pk_mul_f32 v[188:189], v[112:113], v[188:189]
	v_cvt_pk_bf16_f32 v190, v182, v183
	v_cvt_pk_bf16_f32 v191, v184, v185
	v_cvt_pk_bf16_f32 v192, v186, v187
	v_cvt_pk_bf16_f32 v193, v188, v189
	ds_bpermute_b32 v194, v241, v190
	ds_bpermute_b32 v195, v241, v191
	ds_bpermute_b32 v196, v241, v192
	ds_bpermute_b32 v197, v241, v193
	s_waitcnt lgkmcnt(4)
	global_store_dwordx4 v[142:143], v[250:253], off offset:256 nt
	v_cvt_f32_ubyte0_e32 v222, v160
	v_cvt_f32_ubyte1_e32 v223, v160
	v_cvt_f32_ubyte2_e32 v224, v160
	v_cvt_f32_ubyte3_e32 v225, v160
	v_cvt_f32_ubyte0_e32 v226, v161
	v_cvt_f32_ubyte1_e32 v227, v161
	v_cvt_f32_ubyte2_e32 v228, v161
	v_cvt_f32_ubyte3_e32 v229, v161
	v_pk_mul_f32 v[222:223], v[222:223], s[20:21] op_sel_hi:[1,0]
	v_pk_mul_f32 v[224:225], v[224:225], s[20:21] op_sel_hi:[1,0]
	v_pk_mul_f32 v[226:227], v[226:227], s[20:21] op_sel_hi:[1,0]
	v_pk_mul_f32 v[228:229], v[228:229], s[20:21] op_sel_hi:[1,0]
	v_pk_mul_f32 v[222:223], v[82:83], v[222:223]
	v_pk_mul_f32 v[224:225], v[84:85], v[224:225]
	v_pk_mul_f32 v[226:227], v[78:79], v[226:227]
	v_pk_mul_f32 v[228:229], v[80:81], v[228:229]
	v_cvt_pk_bf16_f32 v144, v222, v223
	v_cvt_pk_bf16_f32 v145, v224, v225
	v_cvt_pk_bf16_f32 v146, v226, v227
	v_cvt_pk_bf16_f32 v147, v228, v229
	ds_bpermute_b32 v250, v241, v144
	ds_bpermute_b32 v251, v241, v145
	ds_bpermute_b32 v252, v241, v146
	ds_bpermute_b32 v253, v241, v147
	s_waitcnt lgkmcnt(4)
	global_store_dwordx4 v[140:141], v[194:197], off nt
	s_mov_b64 s[2:3], 0x18000
	v_lshl_add_u64 v[142:143], v[138:139], 0, s[2:3]
	v_cvt_f32_ubyte0_e32 v182, v162
	v_cvt_f32_ubyte1_e32 v183, v162
	v_cvt_f32_ubyte2_e32 v184, v162
	v_cvt_f32_ubyte3_e32 v185, v162
	v_cvt_f32_ubyte0_e32 v186, v163
	v_cvt_f32_ubyte1_e32 v187, v163
	v_cvt_f32_ubyte2_e32 v188, v163
	v_cvt_f32_ubyte3_e32 v189, v163
	v_pk_mul_f32 v[182:183], v[182:183], s[20:21] op_sel_hi:[1,0]
	v_pk_mul_f32 v[184:185], v[184:185], s[20:21] op_sel_hi:[1,0]
	v_pk_mul_f32 v[186:187], v[186:187], s[20:21] op_sel_hi:[1,0]
	v_pk_mul_f32 v[188:189], v[188:189], s[20:21] op_sel_hi:[1,0]
	v_pk_mul_f32 v[182:183], v[106:107], v[182:183]
	v_pk_mul_f32 v[184:185], v[108:109], v[184:185]
	v_pk_mul_f32 v[186:187], v[102:103], v[186:187]
	v_pk_mul_f32 v[188:189], v[104:105], v[188:189]
	v_cvt_pk_bf16_f32 v190, v182, v183
	v_cvt_pk_bf16_f32 v191, v184, v185
	v_cvt_pk_bf16_f32 v192, v186, v187
	v_cvt_pk_bf16_f32 v193, v188, v189
	ds_bpermute_b32 v194, v241, v190
	ds_bpermute_b32 v195, v241, v191
	ds_bpermute_b32 v196, v241, v192
	ds_bpermute_b32 v197, v241, v193
	s_waitcnt lgkmcnt(4)
	global_store_dwordx4 v[140:141], v[250:253], off offset:256 nt
	v_cvt_f32_ubyte0_e32 v222, v164
	v_cvt_f32_ubyte1_e32 v223, v164
	v_cvt_f32_ubyte2_e32 v224, v164
	v_cvt_f32_ubyte3_e32 v225, v164
	v_cvt_f32_ubyte0_e32 v226, v165
	v_cvt_f32_ubyte1_e32 v227, v165
	v_cvt_f32_ubyte2_e32 v228, v165
	v_cvt_f32_ubyte3_e32 v229, v165
	v_pk_mul_f32 v[222:223], v[222:223], s[20:21] op_sel_hi:[1,0]
	v_pk_mul_f32 v[224:225], v[224:225], s[20:21] op_sel_hi:[1,0]
	v_pk_mul_f32 v[226:227], v[226:227], s[20:21] op_sel_hi:[1,0]
	v_pk_mul_f32 v[228:229], v[228:229], s[20:21] op_sel_hi:[1,0]
	v_pk_mul_f32 v[222:223], v[74:75], v[222:223]
	v_pk_mul_f32 v[224:225], v[76:77], v[224:225]
	v_pk_mul_f32 v[226:227], v[70:71], v[226:227]
	v_pk_mul_f32 v[228:229], v[72:73], v[228:229]
	v_cvt_pk_bf16_f32 v144, v222, v223
	v_cvt_pk_bf16_f32 v145, v224, v225
	v_cvt_pk_bf16_f32 v146, v226, v227
	v_cvt_pk_bf16_f32 v147, v228, v229
	ds_bpermute_b32 v250, v241, v144
	ds_bpermute_b32 v251, v241, v145
	ds_bpermute_b32 v252, v241, v146
	ds_bpermute_b32 v253, v241, v147
	s_waitcnt lgkmcnt(4)
	global_store_dwordx4 v[142:143], v[194:197], off nt
	s_mov_b64 s[2:3], 0x40000
	v_lshl_add_u64 v[140:141], v[138:139], 0, s[2:3]
	v_cvt_f32_ubyte0_e32 v182, v166
	v_cvt_f32_ubyte1_e32 v183, v166
	v_cvt_f32_ubyte2_e32 v184, v166
	v_cvt_f32_ubyte3_e32 v185, v166
	v_cvt_f32_ubyte0_e32 v186, v167
	v_cvt_f32_ubyte1_e32 v187, v167
	v_cvt_f32_ubyte2_e32 v188, v167
	v_cvt_f32_ubyte3_e32 v189, v167
	v_pk_mul_f32 v[182:183], v[182:183], s[20:21] op_sel_hi:[1,0]
	v_pk_mul_f32 v[184:185], v[184:185], s[20:21] op_sel_hi:[1,0]
	v_pk_mul_f32 v[186:187], v[186:187], s[20:21] op_sel_hi:[1,0]
	v_pk_mul_f32 v[188:189], v[188:189], s[20:21] op_sel_hi:[1,0]
	v_pk_mul_f32 v[182:183], v[66:67], v[182:183]
	v_pk_mul_f32 v[184:185], v[68:69], v[184:185]
	v_pk_mul_f32 v[186:187], v[62:63], v[186:187]
	v_pk_mul_f32 v[188:189], v[64:65], v[188:189]
	v_cvt_pk_bf16_f32 v190, v182, v183
	v_cvt_pk_bf16_f32 v191, v184, v185
	v_cvt_pk_bf16_f32 v192, v186, v187
	v_cvt_pk_bf16_f32 v193, v188, v189
	ds_bpermute_b32 v194, v241, v190
	ds_bpermute_b32 v195, v241, v191
	ds_bpermute_b32 v196, v241, v192
	ds_bpermute_b32 v197, v241, v193
	s_waitcnt lgkmcnt(4)
	global_store_dwordx4 v[142:143], v[250:253], off offset:256 nt
	v_cvt_f32_ubyte0_e32 v222, v168
	v_cvt_f32_ubyte1_e32 v223, v168
	v_cvt_f32_ubyte2_e32 v224, v168
	v_cvt_f32_ubyte3_e32 v225, v168
	v_cvt_f32_ubyte0_e32 v226, v169
	v_cvt_f32_ubyte1_e32 v227, v169
	v_cvt_f32_ubyte2_e32 v228, v169
	v_cvt_f32_ubyte3_e32 v229, v169
	v_pk_mul_f32 v[222:223], v[222:223], s[20:21] op_sel_hi:[1,0]
	v_pk_mul_f32 v[224:225], v[224:225], s[20:21] op_sel_hi:[1,0]
	v_pk_mul_f32 v[226:227], v[226:227], s[20:21] op_sel_hi:[1,0]
	v_pk_mul_f32 v[228:229], v[228:229], s[20:21] op_sel_hi:[1,0]
	v_pk_mul_f32 v[222:223], v[34:35], v[222:223]
	v_pk_mul_f32 v[224:225], v[36:37], v[224:225]
	v_pk_mul_f32 v[226:227], v[30:31], v[226:227]
	v_pk_mul_f32 v[228:229], v[32:33], v[228:229]
	v_cvt_pk_bf16_f32 v144, v222, v223
	v_cvt_pk_bf16_f32 v145, v224, v225
	v_cvt_pk_bf16_f32 v146, v226, v227
	v_cvt_pk_bf16_f32 v147, v228, v229
	ds_bpermute_b32 v250, v241, v144
	ds_bpermute_b32 v251, v241, v145
	ds_bpermute_b32 v252, v241, v146
	ds_bpermute_b32 v253, v241, v147
	s_waitcnt lgkmcnt(4)
	global_store_dwordx4 v[140:141], v[194:197], off nt
	s_mov_b64 s[2:3], 0x48000
	v_lshl_add_u64 v[142:143], v[138:139], 0, s[2:3]
	v_cvt_f32_ubyte0_e32 v182, v170
	v_cvt_f32_ubyte1_e32 v183, v170
	v_cvt_f32_ubyte2_e32 v184, v170
	v_cvt_f32_ubyte3_e32 v185, v170
	v_cvt_f32_ubyte0_e32 v186, v171
	v_cvt_f32_ubyte1_e32 v187, v171
	v_cvt_f32_ubyte2_e32 v188, v171
	v_cvt_f32_ubyte3_e32 v189, v171
	v_pk_mul_f32 v[182:183], v[182:183], s[20:21] op_sel_hi:[1,0]
	v_pk_mul_f32 v[184:185], v[184:185], s[20:21] op_sel_hi:[1,0]
	v_pk_mul_f32 v[186:187], v[186:187], s[20:21] op_sel_hi:[1,0]
	v_pk_mul_f32 v[188:189], v[188:189], s[20:21] op_sel_hi:[1,0]
	v_pk_mul_f32 v[182:183], v[58:59], v[182:183]
	v_pk_mul_f32 v[184:185], v[60:61], v[184:185]
	v_pk_mul_f32 v[186:187], v[54:55], v[186:187]
	v_pk_mul_f32 v[188:189], v[56:57], v[188:189]
	v_cvt_pk_bf16_f32 v190, v182, v183
	v_cvt_pk_bf16_f32 v191, v184, v185
	v_cvt_pk_bf16_f32 v192, v186, v187
	v_cvt_pk_bf16_f32 v193, v188, v189
	ds_bpermute_b32 v194, v241, v190
	ds_bpermute_b32 v195, v241, v191
	ds_bpermute_b32 v196, v241, v192
	ds_bpermute_b32 v197, v241, v193
	s_waitcnt lgkmcnt(4)
	global_store_dwordx4 v[140:141], v[250:253], off offset:256 nt
	v_cvt_f32_ubyte0_e32 v222, v172
	v_cvt_f32_ubyte1_e32 v223, v172
	v_cvt_f32_ubyte2_e32 v224, v172
	v_cvt_f32_ubyte3_e32 v225, v172
	v_cvt_f32_ubyte0_e32 v226, v173
	v_cvt_f32_ubyte1_e32 v227, v173
	v_cvt_f32_ubyte2_e32 v228, v173
	v_cvt_f32_ubyte3_e32 v229, v173
	v_pk_mul_f32 v[222:223], v[222:223], s[20:21] op_sel_hi:[1,0]
	v_pk_mul_f32 v[224:225], v[224:225], s[20:21] op_sel_hi:[1,0]
	v_pk_mul_f32 v[226:227], v[226:227], s[20:21] op_sel_hi:[1,0]
	v_pk_mul_f32 v[228:229], v[228:229], s[20:21] op_sel_hi:[1,0]
	v_pk_mul_f32 v[222:223], v[26:27], v[222:223]
	v_pk_mul_f32 v[224:225], v[28:29], v[224:225]
	v_pk_mul_f32 v[226:227], v[22:23], v[226:227]
	v_pk_mul_f32 v[228:229], v[24:25], v[228:229]
	v_cvt_pk_bf16_f32 v144, v222, v223
	v_cvt_pk_bf16_f32 v145, v224, v225
	v_cvt_pk_bf16_f32 v146, v226, v227
	v_cvt_pk_bf16_f32 v147, v228, v229
	ds_bpermute_b32 v250, v241, v144
	ds_bpermute_b32 v251, v241, v145
	ds_bpermute_b32 v252, v241, v146
	ds_bpermute_b32 v253, v241, v147
	s_waitcnt lgkmcnt(4)
	global_store_dwordx4 v[142:143], v[194:197], off nt
	s_mov_b64 s[2:3], 0x50000
	v_lshl_add_u64 v[140:141], v[138:139], 0, s[2:3]
	v_cvt_f32_ubyte0_e32 v182, v174
	v_cvt_f32_ubyte1_e32 v183, v174
	v_cvt_f32_ubyte2_e32 v184, v174
	v_cvt_f32_ubyte3_e32 v185, v174
	v_cvt_f32_ubyte0_e32 v186, v175
	v_cvt_f32_ubyte1_e32 v187, v175
	v_cvt_f32_ubyte2_e32 v188, v175
	v_cvt_f32_ubyte3_e32 v189, v175
	v_pk_mul_f32 v[182:183], v[182:183], s[20:21] op_sel_hi:[1,0]
	v_pk_mul_f32 v[184:185], v[184:185], s[20:21] op_sel_hi:[1,0]
	v_pk_mul_f32 v[186:187], v[186:187], s[20:21] op_sel_hi:[1,0]
	v_pk_mul_f32 v[188:189], v[188:189], s[20:21] op_sel_hi:[1,0]
	v_pk_mul_f32 v[182:183], v[50:51], v[182:183]
	v_pk_mul_f32 v[184:185], v[52:53], v[184:185]
	v_pk_mul_f32 v[186:187], v[46:47], v[186:187]
	v_pk_mul_f32 v[188:189], v[48:49], v[188:189]
	v_cvt_pk_bf16_f32 v190, v182, v183
	v_cvt_pk_bf16_f32 v191, v184, v185
	v_cvt_pk_bf16_f32 v192, v186, v187
	v_cvt_pk_bf16_f32 v193, v188, v189
	ds_bpermute_b32 v194, v241, v190
	ds_bpermute_b32 v195, v241, v191
	ds_bpermute_b32 v196, v241, v192
	ds_bpermute_b32 v197, v241, v193
	s_waitcnt lgkmcnt(4)
	global_store_dwordx4 v[142:143], v[250:253], off offset:256 nt
	v_cvt_f32_ubyte0_e32 v222, v176
	v_cvt_f32_ubyte1_e32 v223, v176
	v_cvt_f32_ubyte2_e32 v224, v176
	v_cvt_f32_ubyte3_e32 v225, v176
	v_cvt_f32_ubyte0_e32 v226, v177
	v_cvt_f32_ubyte1_e32 v227, v177
	v_cvt_f32_ubyte2_e32 v228, v177
	v_cvt_f32_ubyte3_e32 v229, v177
	v_pk_mul_f32 v[222:223], v[222:223], s[20:21] op_sel_hi:[1,0]
	v_pk_mul_f32 v[224:225], v[224:225], s[20:21] op_sel_hi:[1,0]
	v_pk_mul_f32 v[226:227], v[226:227], s[20:21] op_sel_hi:[1,0]
	v_pk_mul_f32 v[228:229], v[228:229], s[20:21] op_sel_hi:[1,0]
	v_pk_mul_f32 v[222:223], v[18:19], v[222:223]
	v_pk_mul_f32 v[224:225], v[20:21], v[224:225]
	v_pk_mul_f32 v[226:227], v[14:15], v[226:227]
	v_pk_mul_f32 v[228:229], v[16:17], v[228:229]
	v_cvt_pk_bf16_f32 v144, v222, v223
	v_cvt_pk_bf16_f32 v145, v224, v225
	v_cvt_pk_bf16_f32 v146, v226, v227
	v_cvt_pk_bf16_f32 v147, v228, v229
	ds_bpermute_b32 v250, v241, v144
	ds_bpermute_b32 v251, v241, v145
	ds_bpermute_b32 v252, v241, v146
	ds_bpermute_b32 v253, v241, v147
	s_waitcnt lgkmcnt(4)
	global_store_dwordx4 v[140:141], v[194:197], off nt
	s_mov_b64 s[2:3], 0x58000
	v_lshl_add_u64 v[142:143], v[138:139], 0, s[2:3]
	v_cvt_f32_ubyte0_e32 v182, v178
	v_cvt_f32_ubyte1_e32 v183, v178
	v_cvt_f32_ubyte2_e32 v184, v178
	v_cvt_f32_ubyte3_e32 v185, v178
	v_cvt_f32_ubyte0_e32 v186, v179
	v_cvt_f32_ubyte1_e32 v187, v179
	v_cvt_f32_ubyte2_e32 v188, v179
	v_cvt_f32_ubyte3_e32 v189, v179
	v_pk_mul_f32 v[182:183], v[182:183], s[20:21] op_sel_hi:[1,0]
	v_pk_mul_f32 v[184:185], v[184:185], s[20:21] op_sel_hi:[1,0]
	v_pk_mul_f32 v[186:187], v[186:187], s[20:21] op_sel_hi:[1,0]
	v_pk_mul_f32 v[188:189], v[188:189], s[20:21] op_sel_hi:[1,0]
	v_pk_mul_f32 v[182:183], v[42:43], v[182:183]
	v_pk_mul_f32 v[184:185], v[44:45], v[184:185]
	v_pk_mul_f32 v[186:187], v[38:39], v[186:187]
	v_pk_mul_f32 v[188:189], v[40:41], v[188:189]
	v_cvt_pk_bf16_f32 v190, v182, v183
	v_cvt_pk_bf16_f32 v191, v184, v185
	v_cvt_pk_bf16_f32 v192, v186, v187
	v_cvt_pk_bf16_f32 v193, v188, v189
	ds_bpermute_b32 v194, v241, v190
	ds_bpermute_b32 v195, v241, v191
	ds_bpermute_b32 v196, v241, v192
	ds_bpermute_b32 v197, v241, v193
	s_waitcnt lgkmcnt(4)
	global_store_dwordx4 v[140:141], v[250:253], off offset:256 nt
	v_cvt_f32_ubyte0_e32 v222, v180
	v_cvt_f32_ubyte1_e32 v223, v180
	v_cvt_f32_ubyte2_e32 v224, v180
	v_cvt_f32_ubyte3_e32 v225, v180
	v_cvt_f32_ubyte0_e32 v226, v181
	v_cvt_f32_ubyte1_e32 v227, v181
	v_cvt_f32_ubyte2_e32 v228, v181
	v_cvt_f32_ubyte3_e32 v229, v181
	v_pk_mul_f32 v[222:223], v[222:223], s[20:21] op_sel_hi:[1,0]
	v_pk_mul_f32 v[224:225], v[224:225], s[20:21] op_sel_hi:[1,0]
	v_pk_mul_f32 v[226:227], v[226:227], s[20:21] op_sel_hi:[1,0]
	v_pk_mul_f32 v[228:229], v[228:229], s[20:21] op_sel_hi:[1,0]
	v_pk_mul_f32 v[222:223], v[10:11], v[222:223]
	v_pk_mul_f32 v[224:225], v[12:13], v[224:225]
	v_pk_mul_f32 v[226:227], v[6:7], v[226:227]
	v_pk_mul_f32 v[228:229], v[8:9], v[228:229]
	v_cvt_pk_bf16_f32 v144, v222, v223
	v_cvt_pk_bf16_f32 v145, v224, v225
	v_cvt_pk_bf16_f32 v146, v226, v227
	v_cvt_pk_bf16_f32 v147, v228, v229
	ds_bpermute_b32 v250, v241, v144
	ds_bpermute_b32 v251, v241, v145
	ds_bpermute_b32 v252, v241, v146
	ds_bpermute_b32 v253, v241, v147
	s_waitcnt lgkmcnt(4)
	global_store_dwordx4 v[142:143], v[194:197], off nt
	s_waitcnt lgkmcnt(0)
	global_store_dwordx4 v[142:143], v[250:253], off offset:256 nt
	s_cbranch_execnz .LBB0_552
